# prep: x->bf16 conversion units processed four per iteration (8 loads in flight per lane)
# baseline (speedup 1.0000x reference)
; DI unsigned pack2(float a, float b) { fl2_t v = {a, b}; return __builtin_bit_cast(unsigned, __builtin_convertvector(v, bf2_t)); }
; PH void phase_prep(const Params& p) {
;     ...
;   for (int u = blockIdx.x; u < U_TOT; u += gridDim.x) {
;     ...
;     } else if (u < U_WIN + U_WOUT + U_LW + U_XB) {
;       const int v = u - U_WIN - U_WOUT - U_LW;
;       const size_t ge = (size_t)v * 2048 + (size_t)tid * 8;
;       const float* src = (ge < (size_t)MP * 1024) ? (p.in[0] + ge) : (p.in[1] + (ge - (size_t)MP * 1024));
;       const float4 a = *(const float4*)src, b = *(const float4*)(src + 4);
;       uint4 o; o.x = pack2(a.x, a.y); o.y = pack2(a.z, a.w); o.z = pack2(b.x, b.y); o.w = pack2(b.z, b.w);
;       *(uint4*)(Xb + ge) = o;
.LBB0_43:
	s_andn2_b64 vcc, exec, s[8:9]
	s_cbranch_vccnz .LBB0_45
	s_mul_i32 s84, s64, 3
	s_add_i32 s84, s84, s18
	s_cmpk_gt_i32 s84, 0x3bff
	s_cbranch_scc1 .Lxb_single
	v_readlane_b32 s68, v252, 5
	v_readlane_b32 s69, v252, 6
	v_readlane_b32 s70, v252, 7
	v_readlane_b32 s71, v252, 8
	v_readlane_b32 s72, v252, 9
	v_readlane_b32 s73, v252, 10
	v_readlane_b32 s74, v252, 11
	v_readlane_b32 s75, v252, 12
	v_readlane_b32 s76, v252, 13
	v_readlane_b32 s77, v252, 14
	v_readlane_b32 s78, v252, 15
	v_readlane_b32 s79, v252, 16
	v_readlane_b32 s80, v252, 17
	v_readlane_b32 s81, v252, 18
	v_readlane_b32 s82, v252, 19
	v_readlane_b32 s83, v252, 20
	v_readlane_b32 s96, v252, 55
	v_readlane_b32 s97, v252, 56
	v_lshlrev_b32_e32 v96, 2, v10
	v_lshlrev_b32_e32 v97, 1, v10
	s_add_i32 s28, s18, 0xffffe440
	s_mov_b32 s9, s28
	s_cmp_lt_u32 s28, 0x2000
	s_cselect_b32 s84, s68, s70
	s_cselect_b32 s85, s69, s71
	s_cselect_b32 s8, 0, 0x2000
	s_sub_i32 s8, s28, s8
	s_lshl_b32 s8, s8, 13
	s_add_u32 s84, s84, s8
	s_addc_u32 s85, s85, 0
	global_load_dwordx4 v[100:103], v96, s[84:85]
	global_load_dwordx4 v[104:107], v96, s[84:85] offset:16
	s_add_i32 s28, s28, s64
	s_cmp_lt_u32 s28, 0x2000
	s_cselect_b32 s86, s68, s70
	s_cselect_b32 s87, s69, s71
	s_cselect_b32 s8, 0, 0x2000
	s_sub_i32 s8, s28, s8
	s_lshl_b32 s8, s8, 13
	s_add_u32 s86, s86, s8
	s_addc_u32 s87, s87, 0
	global_load_dwordx4 v[108:111], v96, s[86:87]
	global_load_dwordx4 v[112:115], v96, s[86:87] offset:16
	s_add_i32 s28, s28, s64
	s_cmp_lt_u32 s28, 0x2000
	s_cselect_b32 s98, s68, s70
	s_cselect_b32 s99, s69, s71
	s_cselect_b32 s8, 0, 0x2000
	s_sub_i32 s8, s28, s8
	s_lshl_b32 s8, s8, 13
	s_add_u32 s98, s98, s8
	s_addc_u32 s99, s99, 0
	global_load_dwordx4 v[116:119], v96, s[98:99]
	global_load_dwordx4 v[120:123], v96, s[98:99] offset:16
	s_add_i32 s28, s28, s64
	s_cmp_lt_u32 s28, 0x2000
	s_cselect_b32 s32, s68, s70
	s_cselect_b32 s33, s69, s71
	s_cselect_b32 s8, 0, 0x2000
	s_sub_i32 s8, s28, s8
	s_lshl_b32 s8, s8, 13
	s_add_u32 s32, s32, s8
	s_addc_u32 s33, s33, 0
	global_load_dwordx4 v[124:127], v96, s[32:33]
	global_load_dwordx4 v[128:131], v96, s[32:33] offset:16
	s_add_i32 s28, s28, s64
	s_lshl_b32 s8, s9, 12
	s_add_u32 s84, s96, s8
	s_addc_u32 s85, s97, 0
	s_waitcnt vmcnt(6)
	v_cvt_pk_bf16_f32 v132, v100, v101
	v_cvt_pk_bf16_f32 v133, v102, v103
	v_cvt_pk_bf16_f32 v134, v104, v105
	v_cvt_pk_bf16_f32 v135, v106, v107
	global_store_dwordx4 v97, v[132:135], s[84:85]
	s_add_i32 s9, s9, s64
	s_lshl_b32 s8, s9, 12
	s_add_u32 s86, s96, s8
	s_addc_u32 s87, s97, 0
	s_waitcnt vmcnt(5)
	v_cvt_pk_bf16_f32 v136, v108, v109
	v_cvt_pk_bf16_f32 v137, v110, v111
	v_cvt_pk_bf16_f32 v138, v112, v113
	v_cvt_pk_bf16_f32 v139, v114, v115
	global_store_dwordx4 v97, v[136:139], s[86:87]
	s_add_i32 s9, s9, s64
	s_lshl_b32 s8, s9, 12
	s_add_u32 s98, s96, s8
	s_addc_u32 s99, s97, 0
	s_waitcnt vmcnt(4)
	v_cvt_pk_bf16_f32 v140, v116, v117
	v_cvt_pk_bf16_f32 v141, v118, v119
	v_cvt_pk_bf16_f32 v142, v120, v121
	v_cvt_pk_bf16_f32 v143, v122, v123
	global_store_dwordx4 v97, v[140:143], s[98:99]
	s_add_i32 s9, s9, s64
	s_lshl_b32 s8, s9, 12
	s_add_u32 s32, s96, s8
	s_addc_u32 s33, s97, 0
	s_waitcnt vmcnt(3)
	v_cvt_pk_bf16_f32 v144, v124, v125
	v_cvt_pk_bf16_f32 v145, v126, v127
	v_cvt_pk_bf16_f32 v146, v128, v129
	v_cvt_pk_bf16_f32 v147, v130, v131
	global_store_dwordx4 v97, v[144:147], s[32:33]
	s_add_i32 s9, s9, s64
	s_mul_i32 s8, s64, 3
	s_add_i32 s18, s18, s8
	s_add_i32 s12, s12, s8
	s_branch .LBB0_45
	s_nop 0
	s_nop 0
	s_nop 0
	s_nop 0
	s_nop 0
	s_nop 0
	s_nop 0
	s_nop 0
	s_nop 0
	s_nop 0
	s_nop 0
	s_nop 0
	s_nop 0
	s_nop 0
	s_nop 0
	s_nop 0
.Lxb_single:
	s_add_i32 s28, s18, 0xffffe440
	s_lshl_b64 s[8:9], s[28:29], 11
	v_lshl_add_u64 v[34:35], s[8:9], 0, v[10:11]
	v_readlane_b32 s68, v252, 5
	v_lshlrev_b64 v[30:31], 2, v[34:35]
	v_readlane_b32 s69, v252, 6
	v_readlane_b32 s70, v252, 7
	v_readlane_b32 s71, v252, 8
	s_brev_b32 s8, 63
	v_lshl_add_u64 v[32:33], s[68:69], 0, v[30:31]
	v_lshl_add_u64 v[30:31], s[70:71], 0, v[30:31]
	s_mov_b32 s9, -1
	v_lshl_add_u64 v[30:31], v[30:31], 0, s[8:9]
	s_mov_b64 s[8:9], 0x1000000
	v_cmp_gt_u64_e32 vcc, s[8:9], v[34:35]
	v_readlane_b32 s8, v252, 55
	v_readlane_b32 s9, v252, 56
	v_cndmask_b32_e32 v71, v31, v33, vcc
	v_cndmask_b32_e32 v70, v30, v32, vcc
	global_load_dwordx4 v[30:33], v[70:71], off
	s_nop 0
	global_load_dwordx4 v[70:73], v[70:71], off offset:16
	v_lshl_add_u64 v[34:35], v[34:35], 1, s[8:9]
	v_readlane_b32 s72, v252, 9
	v_readlane_b32 s73, v252, 10
	v_readlane_b32 s74, v252, 11
	v_readlane_b32 s75, v252, 12
	v_readlane_b32 s76, v252, 13
	v_readlane_b32 s77, v252, 14
	v_readlane_b32 s78, v252, 15
	v_readlane_b32 s79, v252, 16
	v_readlane_b32 s80, v252, 17
	v_readlane_b32 s81, v252, 18
	v_readlane_b32 s82, v252, 19
	v_readlane_b32 s83, v252, 20
	s_waitcnt vmcnt(1)
	v_cvt_pk_bf16_f32 v30, v30, v31
	v_cvt_pk_bf16_f32 v31, v32, v33
	s_waitcnt vmcnt(0)
	v_cvt_pk_bf16_f32 v32, v70, v71
	v_cvt_pk_bf16_f32 v33, v72, v73
	global_store_dwordx4 v[34:35], v[30:33], off
